# v10 + the trailing grid barrier after the last layer's final phase is skipped (waves end right after their last stores)
# speedup vs baseline: 1.0067x; 1.0067x over previous
; #define GSYNC() do { XcdBarrier xb_; xb_.bar = (unsigned*)load_args(ap).ws; xb_.x = xb_xcc_id(); xb_.st = (volatile LAS unsigned*)(lds + LDS_BYTES - 16); xcd_barrier(xb_, opaque_tid(wv) == 0); } while (0)
; #define PH(b) if constexpr ((PH_MASK >> (b)) & 1)
; #define REP(b) for (int rep_ = ((DUP_MASK >> (b)) & 1) ? 0 : 1; rep_ < 2; ++rep_)
; __global__ void __launch_bounds__(NTHR, 2) fwd_kernel(Args a_unused) {
;     ...
;         PH(13) REP(13) { LOADARGS; pg8::Gemm g{HID, (const bf16_t*)(ws + W_2O), MTOK, DM, DFF}; pg8::StaticOrder S; S.init(MTOK, DM, G, bid); EpiResid E{a.out, XB, (unsigned char*)(ws + WS_XL), DMY ? (float*)(ws + WS_DUMMY) : ssq3, DMY ? 0.f : 0.5f, l == 1}; pg8::gemm_phase(wv, lds, g, S, E); }
;         GSYNC();
;     }
.LBB0_1110:
	v_readlane_b32 s2, v253, 34
	v_readlane_b32 s3, v253, 35
	s_and_b64 vcc, exec, s[2:3]
	s_cbranch_vccz .Lgs_last_go
	s_endpgm
